# v18 + EVEN_IN epilogue rope ladders de-serialised: the 32 identical cos/sin loads become one preload, the 32 row-dependent ones are issued up front with immediate offsets (one wait per ladder instead
# speedup vs baseline: 1.0071x; 1.0071x over previous
.LBB0_1319:
	s_or_saveexec_b64 s[0:1], s[0:1]
	v_lshlrev_b32_e32 v32, 1, v182
	v_and_b32_e32 v136, 0xc0, v142
	v_and_b32_e32 v137, 30, v32
	s_xor_b64 exec, exec, s[0:1]
	s_cbranch_execz .LBB0_1513
	v_bfe_u32 v236, v142, 6, 4
	v_lshlrev_b32_e32 v237, 2, v137
	v_lshl_or_b32 v236, v236, 7, v237
	global_load_dwordx2 v[236:237], v236, s[74:75]
	v_and_b32_e32 v133, 64, v169
	v_xor_b32_e32 v32, 16, v169
	v_add_u32_e32 v133, 64, v133
	v_cmp_lt_i32_e32 vcc, v32, v133
	v_add_u32_e32 v132, 0xfffffe00, v146
	v_cmp_lt_i32_e64 s[40:41], s72, v143
	v_cndmask_b32_e32 v32, v169, v32, vcc
	v_lshlrev_b32_e32 v139, 2, v32
	ds_bpermute_b32 v32, v139, v50
	v_ashrrev_i32_e32 v133, 31, v132
	s_mov_b64 s[28:29], -1
	s_and_b64 vcc, exec, s[20:21]
	s_cbranch_vccz .LBB0_1324
	s_and_saveexec_b64 s[28:29], s[40:41]
	s_cbranch_execz .LBB0_1323
	v_or3_b32 v134, v136, v140, v130
	v_mov_b32_e32 v135, v131
	v_lshlrev_b64 v[134:135], 9, v[134:135]
	v_lshl_add_u64 v[134:135], s[92:93], 0, v[134:135]
	v_lshl_add_u64 v[134:135], v[132:133], 2, v[134:135]
	v_add_co_u32_e32 v134, vcc, 0x4000000, v134
	s_nop 1
	v_addc_co_u32_e32 v135, vcc, 0, v135, vcc
	global_store_dword v[134:135], v50, off

.LBB0_1324:
	s_andn2_b64 vcc, exec, s[28:29]
	v_bfe_u32 v138, v142, 6, 4
	s_cbranch_vccnz .LBB0_1326
	v_lshlrev_b32_e32 v134, 2, v137
	v_lshl_or_b32 v134, v138, 7, v134
	s_waitcnt vmcnt(0) lgkmcnt(0)
	v_mov_b32_e32 v134, v236
	v_mov_b32_e32 v135, v237
	v_mul_f32_e32 v32, v135, v32
	v_cndmask_b32_e64 v32, v32, -v32, s[38:39]
	v_fmac_f32_e32 v32, v50, v134
	v_mov_b32_e32 v50, v32

.LBB0_1330:
	s_andn2_b64 vcc, exec, s[28:29]
	s_cbranch_vccnz .LBB0_1332
	v_lshlrev_b32_e32 v146, 2, v137
	v_lshl_or_b32 v146, v138, 7, v146
	s_waitcnt lgkmcnt(0)
	v_mov_b32_e32 v148, v236
	v_mov_b32_e32 v149, v237
	v_mul_f32_e32 v50, v149, v50
	v_cndmask_b32_e64 v50, v50, -v50, s[38:39]
	v_fmac_f32_e32 v50, v51, v148
	v_mov_b32_e32 v51, v50

.LBB0_1336:
	s_andn2_b64 vcc, exec, s[28:29]
	s_cbranch_vccnz .LBB0_1338
	v_lshlrev_b32_e32 v51, 2, v137
	v_lshl_or_b32 v51, v138, 7, v51
	s_waitcnt lgkmcnt(0)
	v_mov_b32_e32 v148, v236
	v_mov_b32_e32 v149, v237
	v_mul_f32_e32 v50, v149, v50
	v_cndmask_b32_e64 v50, v50, -v50, s[38:39]
	v_fmac_f32_e32 v50, v52, v148
	v_mov_b32_e32 v52, v50

.LBB0_1342:
	s_andn2_b64 vcc, exec, s[28:29]
	s_cbranch_vccnz .LBB0_1344
	v_lshlrev_b32_e32 v51, 2, v137
	v_lshl_or_b32 v51, v138, 7, v51
	s_waitcnt lgkmcnt(0)
	v_mov_b32_e32 v148, v236
	v_mov_b32_e32 v149, v237
	v_mul_f32_e32 v50, v149, v50
	v_cndmask_b32_e64 v50, v50, -v50, s[38:39]
	v_fmac_f32_e32 v50, v53, v148
	v_mov_b32_e32 v53, v50

.LBB0_1348:
	s_andn2_b64 vcc, exec, s[28:29]
	s_cbranch_vccnz .LBB0_1350
	v_lshlrev_b32_e32 v51, 2, v137
	v_lshl_or_b32 v51, v138, 7, v51
	s_waitcnt lgkmcnt(0)
	v_mov_b32_e32 v52, v236
	v_mov_b32_e32 v53, v237
	v_mul_f32_e32 v50, v53, v50
	v_cndmask_b32_e64 v50, v50, -v50, s[38:39]
	v_fmac_f32_e32 v50, v54, v52
	v_mov_b32_e32 v54, v50

.LBB0_1354:
	s_andn2_b64 vcc, exec, s[28:29]
	s_cbranch_vccnz .LBB0_1356
	v_lshlrev_b32_e32 v51, 2, v137
	v_lshl_or_b32 v51, v138, 7, v51
	s_waitcnt lgkmcnt(0)
	v_mov_b32_e32 v52, v236
	v_mov_b32_e32 v53, v237
	v_mul_f32_e32 v50, v53, v50
	v_cndmask_b32_e64 v50, v50, -v50, s[38:39]
	v_fmac_f32_e32 v50, v55, v52
	v_mov_b32_e32 v55, v50

.LBB0_1360:
	s_andn2_b64 vcc, exec, s[28:29]
	s_cbranch_vccnz .LBB0_1362
	v_lshlrev_b32_e32 v51, 2, v137
	v_lshl_or_b32 v51, v138, 7, v51
	s_waitcnt lgkmcnt(0)
	v_mov_b32_e32 v52, v236
	v_mov_b32_e32 v53, v237
	v_mul_f32_e32 v50, v53, v50
	v_cndmask_b32_e64 v50, v50, -v50, s[38:39]
	v_fmac_f32_e32 v50, v56, v52
	v_mov_b32_e32 v56, v50

.LBB0_1366:
	s_andn2_b64 vcc, exec, s[28:29]
	s_cbranch_vccnz .LBB0_1368
	v_lshlrev_b32_e32 v51, 2, v137
	v_lshl_or_b32 v51, v138, 7, v51
	s_waitcnt lgkmcnt(0)
	v_mov_b32_e32 v52, v236
	v_mov_b32_e32 v53, v237
	v_mul_f32_e32 v50, v53, v50
	v_cndmask_b32_e64 v50, v50, -v50, s[38:39]
	v_fmac_f32_e32 v50, v57, v52
	v_mov_b32_e32 v57, v50

.LBB0_1372:
	s_andn2_b64 vcc, exec, s[28:29]
	s_cbranch_vccnz .LBB0_1374
	v_lshlrev_b32_e32 v51, 2, v137
	v_lshl_or_b32 v51, v138, 7, v51
	s_waitcnt lgkmcnt(0)
	v_mov_b32_e32 v52, v236
	v_mov_b32_e32 v53, v237
	v_mul_f32_e32 v50, v53, v50
	v_cndmask_b32_e64 v50, v50, -v50, s[38:39]
	v_fmac_f32_e32 v50, v58, v52
	v_mov_b32_e32 v58, v50

.LBB0_1378:
	s_andn2_b64 vcc, exec, s[28:29]
	s_cbranch_vccnz .LBB0_1380
	v_lshlrev_b32_e32 v51, 2, v137
	v_lshl_or_b32 v51, v138, 7, v51
	s_waitcnt lgkmcnt(0)
	v_mov_b32_e32 v52, v236
	v_mov_b32_e32 v53, v237
	v_mul_f32_e32 v50, v53, v50
	v_cndmask_b32_e64 v50, v50, -v50, s[38:39]
	v_fmac_f32_e32 v50, v59, v52
	v_mov_b32_e32 v59, v50

.LBB0_1384:
	s_andn2_b64 vcc, exec, s[28:29]
	s_cbranch_vccnz .LBB0_1386
	v_lshlrev_b32_e32 v51, 2, v137
	v_lshl_or_b32 v51, v138, 7, v51
	s_waitcnt lgkmcnt(0)
	v_mov_b32_e32 v52, v236
	v_mov_b32_e32 v53, v237
	v_mul_f32_e32 v50, v53, v50
	v_cndmask_b32_e64 v50, v50, -v50, s[38:39]
	v_fmac_f32_e32 v50, v60, v52
	v_mov_b32_e32 v60, v50

.LBB0_1390:
	s_andn2_b64 vcc, exec, s[28:29]
	s_cbranch_vccnz .LBB0_1392
	v_lshlrev_b32_e32 v51, 2, v137
	v_lshl_or_b32 v51, v138, 7, v51
	s_waitcnt lgkmcnt(0)
	v_mov_b32_e32 v52, v236
	v_mov_b32_e32 v53, v237
	v_mul_f32_e32 v50, v53, v50
	v_cndmask_b32_e64 v50, v50, -v50, s[38:39]
	v_fmac_f32_e32 v50, v61, v52
	v_mov_b32_e32 v61, v50

.LBB0_1396:
	s_andn2_b64 vcc, exec, s[28:29]
	s_cbranch_vccnz .LBB0_1398
	v_lshlrev_b32_e32 v51, 2, v137
	v_lshl_or_b32 v51, v138, 7, v51
	s_waitcnt lgkmcnt(0)
	v_mov_b32_e32 v52, v236
	v_mov_b32_e32 v53, v237
	v_mul_f32_e32 v50, v53, v50
	v_cndmask_b32_e64 v50, v50, -v50, s[38:39]
	v_fmac_f32_e32 v50, v62, v52
	v_mov_b32_e32 v62, v50

.LBB0_1402:
	s_andn2_b64 vcc, exec, s[28:29]
	s_cbranch_vccnz .LBB0_1404
	v_lshlrev_b32_e32 v51, 2, v137
	v_lshl_or_b32 v51, v138, 7, v51
	s_waitcnt lgkmcnt(0)
	v_mov_b32_e32 v52, v236
	v_mov_b32_e32 v53, v237
	v_mul_f32_e32 v50, v53, v50
	v_cndmask_b32_e64 v50, v50, -v50, s[38:39]
	v_fmac_f32_e32 v50, v63, v52
	v_mov_b32_e32 v63, v50

.LBB0_1408:
	s_andn2_b64 vcc, exec, s[28:29]
	s_cbranch_vccnz .LBB0_1410
	v_lshlrev_b32_e32 v51, 2, v137
	v_lshl_or_b32 v51, v138, 7, v51
	s_waitcnt lgkmcnt(0)
	v_mov_b32_e32 v52, v236
	v_mov_b32_e32 v53, v237
	v_mul_f32_e32 v50, v53, v50
	v_cndmask_b32_e64 v50, v50, -v50, s[38:39]
	v_fmac_f32_e32 v50, v64, v52
	v_mov_b32_e32 v64, v50

.LBB0_1414:
	s_andn2_b64 vcc, exec, s[28:29]
	s_cbranch_vccnz .LBB0_1416
	v_lshlrev_b32_e32 v51, 2, v137
	v_lshl_or_b32 v51, v138, 7, v51
	s_waitcnt lgkmcnt(0)
	v_mov_b32_e32 v52, v236
	v_mov_b32_e32 v53, v237
	v_mul_f32_e32 v50, v53, v50
	v_cndmask_b32_e64 v50, v50, -v50, s[38:39]
	v_fmac_f32_e32 v50, v65, v52
	v_mov_b32_e32 v65, v50

.LBB0_1420:
	s_andn2_b64 vcc, exec, s[28:29]
	s_cbranch_vccnz .LBB0_1422
	v_lshlrev_b32_e32 v51, 2, v137
	v_lshl_or_b32 v51, v138, 7, v51
	s_waitcnt lgkmcnt(0)
	v_mov_b32_e32 v52, v236
	v_mov_b32_e32 v53, v237
	v_mul_f32_e32 v50, v53, v50
	v_cndmask_b32_e64 v50, v50, -v50, s[38:39]
	v_fmac_f32_e32 v50, v34, v52
	v_mov_b32_e32 v34, v50

.LBB0_1426:
	s_andn2_b64 vcc, exec, s[28:29]
	s_cbranch_vccnz .LBB0_1428
	v_lshlrev_b32_e32 v50, 2, v137
	v_lshl_or_b32 v50, v138, 7, v50
	s_waitcnt lgkmcnt(0)
	v_mov_b32_e32 v50, v236
	v_mov_b32_e32 v51, v237
	v_mul_f32_e32 v34, v51, v34
	v_cndmask_b32_e64 v34, v34, -v34, s[38:39]
	v_fmac_f32_e32 v34, v35, v50
	v_mov_b32_e32 v35, v34

.LBB0_1432:
	s_andn2_b64 vcc, exec, s[28:29]
	s_cbranch_vccnz .LBB0_1434
	v_lshlrev_b32_e32 v35, 2, v137
	v_lshl_or_b32 v35, v138, 7, v35
	s_waitcnt lgkmcnt(0)
	v_mov_b32_e32 v50, v236
	v_mov_b32_e32 v51, v237
	v_mul_f32_e32 v34, v51, v34
	v_cndmask_b32_e64 v34, v34, -v34, s[38:39]
	v_fmac_f32_e32 v34, v36, v50
	v_mov_b32_e32 v36, v34

.LBB0_1438:
	s_andn2_b64 vcc, exec, s[28:29]
	s_cbranch_vccnz .LBB0_1440
	v_lshlrev_b32_e32 v35, 2, v137
	v_lshl_or_b32 v35, v138, 7, v35
	s_waitcnt lgkmcnt(0)
	v_mov_b32_e32 v50, v236
	v_mov_b32_e32 v51, v237
	v_mul_f32_e32 v34, v51, v34
	v_cndmask_b32_e64 v34, v34, -v34, s[38:39]
	v_fmac_f32_e32 v34, v37, v50
	v_mov_b32_e32 v37, v34

.LBB0_1444:
	s_andn2_b64 vcc, exec, s[28:29]
	s_cbranch_vccnz .LBB0_1446
	v_lshlrev_b32_e32 v35, 2, v137
	v_lshl_or_b32 v35, v138, 7, v35
	s_waitcnt lgkmcnt(0)
	v_mov_b32_e32 v36, v236
	v_mov_b32_e32 v37, v237
	v_mul_f32_e32 v34, v37, v34
	v_cndmask_b32_e64 v34, v34, -v34, s[38:39]
	v_fmac_f32_e32 v34, v38, v36
	v_mov_b32_e32 v38, v34

.LBB0_1450:
	s_andn2_b64 vcc, exec, s[28:29]
	s_cbranch_vccnz .LBB0_1452
	v_lshlrev_b32_e32 v35, 2, v137
	v_lshl_or_b32 v35, v138, 7, v35
	s_waitcnt lgkmcnt(0)
	v_mov_b32_e32 v36, v236
	v_mov_b32_e32 v37, v237
	v_mul_f32_e32 v34, v37, v34
	v_cndmask_b32_e64 v34, v34, -v34, s[38:39]
	v_fmac_f32_e32 v34, v39, v36
	v_mov_b32_e32 v39, v34

.LBB0_1456:
	s_andn2_b64 vcc, exec, s[28:29]
	s_cbranch_vccnz .LBB0_1458
	v_lshlrev_b32_e32 v35, 2, v137
	v_lshl_or_b32 v35, v138, 7, v35
	s_waitcnt lgkmcnt(0)
	v_mov_b32_e32 v36, v236
	v_mov_b32_e32 v37, v237
	v_mul_f32_e32 v34, v37, v34
	v_cndmask_b32_e64 v34, v34, -v34, s[38:39]
	v_fmac_f32_e32 v34, v40, v36
	v_mov_b32_e32 v40, v34

.LBB0_1462:
	s_andn2_b64 vcc, exec, s[28:29]
	s_cbranch_vccnz .LBB0_1464
	v_lshlrev_b32_e32 v35, 2, v137
	v_lshl_or_b32 v35, v138, 7, v35
	s_waitcnt lgkmcnt(0)
	v_mov_b32_e32 v36, v236
	v_mov_b32_e32 v37, v237
	v_mul_f32_e32 v34, v37, v34
	v_cndmask_b32_e64 v34, v34, -v34, s[38:39]
	v_fmac_f32_e32 v34, v41, v36
	v_mov_b32_e32 v41, v34

.LBB0_1468:
	s_andn2_b64 vcc, exec, s[28:29]
	s_cbranch_vccnz .LBB0_1470
	v_lshlrev_b32_e32 v35, 2, v137
	v_lshl_or_b32 v35, v138, 7, v35
	s_waitcnt lgkmcnt(0)
	v_mov_b32_e32 v36, v236
	v_mov_b32_e32 v37, v237
	v_mul_f32_e32 v34, v37, v34
	v_cndmask_b32_e64 v34, v34, -v34, s[38:39]
	v_fmac_f32_e32 v34, v42, v36
	v_mov_b32_e32 v42, v34

.LBB0_1474:
	s_andn2_b64 vcc, exec, s[28:29]
	s_cbranch_vccnz .LBB0_1476
	v_lshlrev_b32_e32 v35, 2, v137
	v_lshl_or_b32 v35, v138, 7, v35
	s_waitcnt lgkmcnt(0)
	v_mov_b32_e32 v36, v236
	v_mov_b32_e32 v37, v237
	v_mul_f32_e32 v34, v37, v34
	v_cndmask_b32_e64 v34, v34, -v34, s[38:39]
	v_fmac_f32_e32 v34, v43, v36
	v_mov_b32_e32 v43, v34

.LBB0_1480:
	s_andn2_b64 vcc, exec, s[28:29]
	s_cbranch_vccnz .LBB0_1482
	v_lshlrev_b32_e32 v35, 2, v137
	v_lshl_or_b32 v35, v138, 7, v35
	s_waitcnt lgkmcnt(0)
	v_mov_b32_e32 v36, v236
	v_mov_b32_e32 v37, v237
	v_mul_f32_e32 v34, v37, v34
	v_cndmask_b32_e64 v34, v34, -v34, s[38:39]
	v_fmac_f32_e32 v34, v44, v36
	v_mov_b32_e32 v44, v34

.LBB0_1486:
	s_andn2_b64 vcc, exec, s[28:29]
	s_cbranch_vccnz .LBB0_1488
	v_lshlrev_b32_e32 v35, 2, v137
	v_lshl_or_b32 v35, v138, 7, v35
	s_waitcnt lgkmcnt(0)
	v_mov_b32_e32 v36, v236
	v_mov_b32_e32 v37, v237
	v_mul_f32_e32 v34, v37, v34
	v_cndmask_b32_e64 v34, v34, -v34, s[38:39]
	v_fmac_f32_e32 v34, v45, v36
	v_mov_b32_e32 v45, v34

.LBB0_1492:
	s_andn2_b64 vcc, exec, s[28:29]
	s_cbranch_vccnz .LBB0_1494
	v_lshlrev_b32_e32 v35, 2, v137
	v_lshl_or_b32 v35, v138, 7, v35
	s_waitcnt lgkmcnt(0)
	v_mov_b32_e32 v36, v236
	v_mov_b32_e32 v37, v237
	v_mul_f32_e32 v34, v37, v34
	v_cndmask_b32_e64 v34, v34, -v34, s[38:39]
	v_fmac_f32_e32 v34, v46, v36
	v_mov_b32_e32 v46, v34

.LBB0_1498:
	s_andn2_b64 vcc, exec, s[28:29]
	s_cbranch_vccnz .LBB0_1500
	v_lshlrev_b32_e32 v35, 2, v137
	v_lshl_or_b32 v35, v138, 7, v35
	s_waitcnt lgkmcnt(0)
	v_mov_b32_e32 v36, v236
	v_mov_b32_e32 v37, v237
	v_mul_f32_e32 v34, v37, v34
	v_cndmask_b32_e64 v34, v34, -v34, s[38:39]
	v_fmac_f32_e32 v34, v47, v36
	v_mov_b32_e32 v47, v34

.LBB0_1504:
	s_andn2_b64 vcc, exec, s[28:29]
	s_cbranch_vccnz .LBB0_1506
	v_lshlrev_b32_e32 v35, 2, v137
	v_lshl_or_b32 v35, v138, 7, v35
	s_waitcnt lgkmcnt(0)
	v_mov_b32_e32 v36, v236
	v_mov_b32_e32 v37, v237
	v_mul_f32_e32 v34, v37, v34
	v_cndmask_b32_e64 v34, v34, -v34, s[38:39]
	v_fmac_f32_e32 v34, v48, v36
	v_mov_b32_e32 v48, v34

.LBB0_1510:
	s_andn2_b64 vcc, exec, s[28:29]
	s_cbranch_vccnz .LBB0_1512
	v_lshlrev_b32_e32 v35, 2, v137
	v_lshl_or_b32 v35, v138, 7, v35
	s_waitcnt lgkmcnt(0)
	v_mov_b32_e32 v36, v236
	v_mov_b32_e32 v37, v237
	v_mul_f32_e32 v34, v37, v34
	v_cndmask_b32_e64 v34, v34, -v34, s[38:39]
	v_fmac_f32_e32 v34, v49, v36
	v_mov_b32_e32 v49, v34

.LBB0_1553:
	s_andn2_saveexec_b64 s[0:1], s[0:1]
	s_cbranch_execz .LBB0_1186
	v_lshlrev_b32_e32 v132, 2, v137
	v_lshl_or_b32 v132, v180, 9, v132
	v_add_u32_e32 v133, 0x1000, v132
	global_load_dwordx2 v[188:189], v132, s[74:75]
	global_load_dwordx2 v[190:191], v132, s[74:75] offset:128
	global_load_dwordx2 v[192:193], v132, s[74:75] offset:256
	global_load_dwordx2 v[194:195], v132, s[74:75] offset:384
	global_load_dwordx2 v[196:197], v132, s[74:75] offset:1024
	global_load_dwordx2 v[198:199], v132, s[74:75] offset:1152
	global_load_dwordx2 v[200:201], v132, s[74:75] offset:1280
	global_load_dwordx2 v[202:203], v132, s[74:75] offset:1408
	global_load_dwordx2 v[204:205], v132, s[74:75] offset:2048
	global_load_dwordx2 v[206:207], v132, s[74:75] offset:2176
	global_load_dwordx2 v[208:209], v132, s[74:75] offset:2304
	global_load_dwordx2 v[210:211], v132, s[74:75] offset:2432
	global_load_dwordx2 v[212:213], v132, s[74:75] offset:3072
	global_load_dwordx2 v[214:215], v132, s[74:75] offset:3200
	global_load_dwordx2 v[216:217], v132, s[74:75] offset:3328
	global_load_dwordx2 v[218:219], v132, s[74:75] offset:3456
	global_load_dwordx2 v[220:221], v133, s[74:75]
	global_load_dwordx2 v[222:223], v133, s[74:75] offset:128
	global_load_dwordx2 v[236:237], v133, s[74:75] offset:256
	global_load_dwordx2 v[238:239], v133, s[74:75] offset:384
	global_load_dwordx2 v[240:241], v133, s[74:75] offset:1024
	global_load_dwordx2 v[242:243], v133, s[74:75] offset:1152
	global_load_dwordx2 v[244:245], v133, s[74:75] offset:1280
	global_load_dwordx2 v[246:247], v133, s[74:75] offset:1408
	global_load_dwordx2 v[248:249], v133, s[74:75] offset:2048
	global_load_dwordx2 v[250:251], v133, s[74:75] offset:2176
	global_load_dwordx2 v[146:147], v133, s[74:75] offset:2304
	global_load_dwordx2 v[148:149], v133, s[74:75] offset:2432
	global_load_dwordx2 v[150:151], v133, s[74:75] offset:3072
	global_load_dwordx2 v[152:153], v133, s[74:75] offset:3200
	global_load_dwordx2 v[154:155], v133, s[74:75] offset:3328
	global_load_dwordx2 v[156:157], v133, s[74:75] offset:3456
	s_waitcnt vmcnt(0)
	v_and_b32_e32 v36, 64, v169
	v_xor_b32_e32 v35, 16, v169
	v_add_u32_e32 v36, 64, v36
	v_cmp_lt_i32_e32 vcc, v35, v36
	v_add_u32_e32 v34, 0xfffffe00, v41
	v_cndmask_b32_e64 v37, 0, 1, s[20:21]
	v_cndmask_b32_e32 v35, v169, v35, vcc
	v_lshlrev_b32_e32 v38, 2, v35
	ds_bpermute_b32 v36, v38, v16
	v_cmp_lt_i32_e64 s[40:41], s72, v32
	v_ashrrev_i32_e32 v35, 31, v34
	v_cmp_ne_u32_e64 s[42:43], 1, v37
	s_andn2_b64 vcc, exec, s[20:21]
	s_mov_b64 s[20:21], -1
	s_cbranch_vccnz .LBB0_1558
	s_and_saveexec_b64 s[20:21], s[40:41]
	s_cbranch_execz .LBB0_1557
	v_or3_b32 v42, v136, v140, v130
	v_mov_b32_e32 v43, v131
	v_lshlrev_b64 v[42:43], 9, v[42:43]
	v_lshl_add_u64 v[42:43], s[92:93], 0, v[42:43]
	v_lshl_add_u64 v[42:43], v[34:35], 2, v[42:43]
	v_add_co_u32_e32 v42, vcc, 0x4000000, v42
	s_nop 1
	v_addc_co_u32_e32 v43, vcc, 0, v43, vcc
	global_store_dword v[42:43], v16, off

.LBB0_1558:
	s_andn2_b64 vcc, exec, s[20:21]
	v_lshlrev_b32_e32 v39, 2, v137
	s_cbranch_vccnz .LBB0_1560
	v_lshl_or_b32 v37, v180, 9, v39
	s_waitcnt lgkmcnt(0)
	v_mov_b32_e32 v42, v188
	v_mov_b32_e32 v43, v189
	v_mul_f32_e32 v36, v43, v36
	v_cndmask_b32_e64 v36, v36, -v36, s[38:39]
	v_fmac_f32_e32 v36, v16, v42
	v_mov_b32_e32 v16, v36

.LBB0_1564:
	s_andn2_b64 vcc, exec, s[20:21]
	s_cbranch_vccnz .LBB0_1566
	v_lshl_or_b32 v16, v16, 7, v39
	s_waitcnt lgkmcnt(0)
	v_mov_b32_e32 v42, v190
	v_mov_b32_e32 v43, v191
	v_mul_f32_e32 v16, v43, v41
	v_cndmask_b32_e64 v16, v16, -v16, s[38:39]
	v_fmac_f32_e32 v16, v17, v42
	v_mov_b32_e32 v17, v16

.LBB0_1570:
	s_andn2_b64 vcc, exec, s[20:21]
	s_cbranch_vccnz .LBB0_1572
	v_lshl_or_b32 v17, v17, 7, v39
	s_waitcnt lgkmcnt(0)
	v_mov_b32_e32 v42, v192
	v_mov_b32_e32 v43, v193
	v_mul_f32_e32 v16, v43, v16
	v_cndmask_b32_e64 v16, v16, -v16, s[38:39]
	v_fmac_f32_e32 v16, v18, v42
	v_mov_b32_e32 v18, v16

.LBB0_1576:
	s_andn2_b64 vcc, exec, s[20:21]
	s_cbranch_vccnz .LBB0_1578
	v_lshl_or_b32 v17, v17, 7, v39
	s_waitcnt lgkmcnt(0)
	v_mov_b32_e32 v42, v194
	v_mov_b32_e32 v43, v195
	v_mul_f32_e32 v16, v43, v16
	v_cndmask_b32_e64 v16, v16, -v16, s[38:39]
	v_fmac_f32_e32 v16, v19, v42
	v_mov_b32_e32 v19, v16

.LBB0_1582:
	s_andn2_b64 vcc, exec, s[20:21]
	s_cbranch_vccnz .LBB0_1584
	v_lshl_or_b32 v17, v17, 7, v39
	s_waitcnt lgkmcnt(0)
	v_mov_b32_e32 v18, v196
	v_mov_b32_e32 v19, v197
	v_mul_f32_e32 v16, v19, v16
	v_cndmask_b32_e64 v16, v16, -v16, s[38:39]
	v_fmac_f32_e32 v16, v20, v18
	v_mov_b32_e32 v20, v16

.LBB0_1588:
	s_andn2_b64 vcc, exec, s[20:21]
	s_cbranch_vccnz .LBB0_1590
	v_lshl_or_b32 v17, v17, 7, v39
	s_waitcnt lgkmcnt(0)
	v_mov_b32_e32 v18, v198
	v_mov_b32_e32 v19, v199
	v_mul_f32_e32 v16, v19, v16
	v_cndmask_b32_e64 v16, v16, -v16, s[38:39]
	v_fmac_f32_e32 v16, v21, v18
	v_mov_b32_e32 v21, v16

.LBB0_1594:
	s_andn2_b64 vcc, exec, s[20:21]
	s_cbranch_vccnz .LBB0_1596
	v_lshl_or_b32 v17, v17, 7, v39
	s_waitcnt lgkmcnt(0)
	v_mov_b32_e32 v18, v200
	v_mov_b32_e32 v19, v201
	v_mul_f32_e32 v16, v19, v16
	v_cndmask_b32_e64 v16, v16, -v16, s[38:39]
	v_fmac_f32_e32 v16, v22, v18
	v_mov_b32_e32 v22, v16

.LBB0_1600:
	s_andn2_b64 vcc, exec, s[20:21]
	s_cbranch_vccnz .LBB0_1602
	v_lshl_or_b32 v17, v17, 7, v39
	s_waitcnt lgkmcnt(0)
	v_mov_b32_e32 v18, v202
	v_mov_b32_e32 v19, v203
	v_mul_f32_e32 v16, v19, v16
	v_cndmask_b32_e64 v16, v16, -v16, s[38:39]
	v_fmac_f32_e32 v16, v23, v18
	v_mov_b32_e32 v23, v16

.LBB0_1606:
	s_andn2_b64 vcc, exec, s[20:21]
	s_cbranch_vccnz .LBB0_1608
	v_lshl_or_b32 v17, v17, 7, v39
	s_waitcnt lgkmcnt(0)
	v_mov_b32_e32 v18, v204
	v_mov_b32_e32 v19, v205
	v_mul_f32_e32 v16, v19, v16
	v_cndmask_b32_e64 v16, v16, -v16, s[38:39]
	v_fmac_f32_e32 v16, v24, v18
	v_mov_b32_e32 v24, v16

.LBB0_1612:
	s_andn2_b64 vcc, exec, s[20:21]
	s_cbranch_vccnz .LBB0_1614
	v_lshl_or_b32 v17, v17, 7, v39
	s_waitcnt lgkmcnt(0)
	v_mov_b32_e32 v18, v206
	v_mov_b32_e32 v19, v207
	v_mul_f32_e32 v16, v19, v16
	v_cndmask_b32_e64 v16, v16, -v16, s[38:39]
	v_fmac_f32_e32 v16, v25, v18
	v_mov_b32_e32 v25, v16

.LBB0_1618:
	s_andn2_b64 vcc, exec, s[20:21]
	s_cbranch_vccnz .LBB0_1620
	v_lshl_or_b32 v17, v17, 7, v39
	s_waitcnt lgkmcnt(0)
	v_mov_b32_e32 v18, v208
	v_mov_b32_e32 v19, v209
	v_mul_f32_e32 v16, v19, v16
	v_cndmask_b32_e64 v16, v16, -v16, s[38:39]
	v_fmac_f32_e32 v16, v26, v18
	v_mov_b32_e32 v26, v16

.LBB0_1624:
	s_andn2_b64 vcc, exec, s[20:21]
	s_cbranch_vccnz .LBB0_1626
	v_lshl_or_b32 v17, v17, 7, v39
	s_waitcnt lgkmcnt(0)
	v_mov_b32_e32 v18, v210
	v_mov_b32_e32 v19, v211
	v_mul_f32_e32 v16, v19, v16
	v_cndmask_b32_e64 v16, v16, -v16, s[38:39]
	v_fmac_f32_e32 v16, v27, v18
	v_mov_b32_e32 v27, v16

.LBB0_1630:
	s_andn2_b64 vcc, exec, s[20:21]
	s_cbranch_vccnz .LBB0_1632
	v_lshl_or_b32 v17, v17, 7, v39
	s_waitcnt lgkmcnt(0)
	v_mov_b32_e32 v18, v212
	v_mov_b32_e32 v19, v213
	v_mul_f32_e32 v16, v19, v16
	v_cndmask_b32_e64 v16, v16, -v16, s[38:39]
	v_fmac_f32_e32 v16, v28, v18
	v_mov_b32_e32 v28, v16

.LBB0_1636:
	s_andn2_b64 vcc, exec, s[20:21]
	s_cbranch_vccnz .LBB0_1638
	v_lshl_or_b32 v17, v17, 7, v39
	s_waitcnt lgkmcnt(0)
	v_mov_b32_e32 v18, v214
	v_mov_b32_e32 v19, v215
	v_mul_f32_e32 v16, v19, v16
	v_cndmask_b32_e64 v16, v16, -v16, s[38:39]
	v_fmac_f32_e32 v16, v29, v18
	v_mov_b32_e32 v29, v16

.LBB0_1642:
	s_andn2_b64 vcc, exec, s[20:21]
	s_cbranch_vccnz .LBB0_1644
	v_lshl_or_b32 v17, v17, 7, v39
	s_waitcnt lgkmcnt(0)
	v_mov_b32_e32 v18, v216
	v_mov_b32_e32 v19, v217
	v_mul_f32_e32 v16, v19, v16
	v_cndmask_b32_e64 v16, v16, -v16, s[38:39]
	v_fmac_f32_e32 v16, v30, v18
	v_mov_b32_e32 v30, v16

.LBB0_1648:
	s_andn2_b64 vcc, exec, s[20:21]
	s_cbranch_vccnz .LBB0_1650
	v_lshl_or_b32 v17, v17, 7, v39
	s_waitcnt lgkmcnt(0)
	v_mov_b32_e32 v18, v218
	v_mov_b32_e32 v19, v219
	v_mul_f32_e32 v16, v19, v16
	v_cndmask_b32_e64 v16, v16, -v16, s[38:39]
	v_fmac_f32_e32 v16, v31, v18
	v_mov_b32_e32 v31, v16

.LBB0_1654:
	s_andn2_b64 vcc, exec, s[20:21]
	s_cbranch_vccnz .LBB0_1656
	v_lshl_or_b32 v17, v17, 7, v39
	s_waitcnt lgkmcnt(0)
	v_mov_b32_e32 v18, v220
	v_mov_b32_e32 v19, v221
	v_mul_f32_e32 v16, v19, v16
	v_cndmask_b32_e64 v16, v16, -v16, s[38:39]
	v_fmac_f32_e32 v16, v0, v18
	v_mov_b32_e32 v0, v16

.LBB0_1660:
	s_andn2_b64 vcc, exec, s[20:21]
	s_cbranch_vccnz .LBB0_1662
	v_lshl_or_b32 v16, v16, 7, v39
	s_waitcnt lgkmcnt(0)
	v_mov_b32_e32 v16, v222
	v_mov_b32_e32 v17, v223
	v_mul_f32_e32 v0, v17, v0
	v_cndmask_b32_e64 v0, v0, -v0, s[38:39]
	v_fmac_f32_e32 v0, v1, v16
	v_mov_b32_e32 v1, v0

.LBB0_1666:
	s_andn2_b64 vcc, exec, s[20:21]
	s_cbranch_vccnz .LBB0_1668
	v_lshl_or_b32 v1, v1, 7, v39
	s_waitcnt lgkmcnt(0)
	v_mov_b32_e32 v16, v236
	v_mov_b32_e32 v17, v237
	v_mul_f32_e32 v0, v17, v0
	v_cndmask_b32_e64 v0, v0, -v0, s[38:39]
	v_fmac_f32_e32 v0, v2, v16
	v_mov_b32_e32 v2, v0

.LBB0_1672:
	s_andn2_b64 vcc, exec, s[20:21]
	s_cbranch_vccnz .LBB0_1674
	v_lshl_or_b32 v1, v1, 7, v39
	s_waitcnt lgkmcnt(0)
	v_mov_b32_e32 v16, v238
	v_mov_b32_e32 v17, v239
	v_mul_f32_e32 v0, v17, v0
	v_cndmask_b32_e64 v0, v0, -v0, s[38:39]
	v_fmac_f32_e32 v0, v3, v16
	v_mov_b32_e32 v3, v0

.LBB0_1678:
	s_andn2_b64 vcc, exec, s[20:21]
	s_cbranch_vccnz .LBB0_1680
	v_lshl_or_b32 v1, v1, 7, v39
	s_waitcnt lgkmcnt(0)
	v_mov_b32_e32 v2, v240
	v_mov_b32_e32 v3, v241
	v_mul_f32_e32 v0, v3, v0
	v_cndmask_b32_e64 v0, v0, -v0, s[38:39]
	v_fmac_f32_e32 v0, v4, v2
	v_mov_b32_e32 v4, v0

.LBB0_1684:
	s_andn2_b64 vcc, exec, s[20:21]
	s_cbranch_vccnz .LBB0_1686
	v_lshl_or_b32 v1, v1, 7, v39
	s_waitcnt lgkmcnt(0)
	v_mov_b32_e32 v2, v242
	v_mov_b32_e32 v3, v243
	v_mul_f32_e32 v0, v3, v0
	v_cndmask_b32_e64 v0, v0, -v0, s[38:39]
	v_fmac_f32_e32 v0, v5, v2
	v_mov_b32_e32 v5, v0

.LBB0_1690:
	s_andn2_b64 vcc, exec, s[20:21]
	s_cbranch_vccnz .LBB0_1692
	v_lshl_or_b32 v1, v1, 7, v39
	s_waitcnt lgkmcnt(0)
	v_mov_b32_e32 v2, v244
	v_mov_b32_e32 v3, v245
	v_mul_f32_e32 v0, v3, v0
	v_cndmask_b32_e64 v0, v0, -v0, s[38:39]
	v_fmac_f32_e32 v0, v6, v2
	v_mov_b32_e32 v6, v0

.LBB0_1696:
	s_andn2_b64 vcc, exec, s[20:21]
	s_cbranch_vccnz .LBB0_1698
	v_lshl_or_b32 v1, v1, 7, v39
	s_waitcnt lgkmcnt(0)
	v_mov_b32_e32 v2, v246
	v_mov_b32_e32 v3, v247
	v_mul_f32_e32 v0, v3, v0
	v_cndmask_b32_e64 v0, v0, -v0, s[38:39]
	v_fmac_f32_e32 v0, v7, v2
	v_mov_b32_e32 v7, v0

.LBB0_1702:
	s_andn2_b64 vcc, exec, s[20:21]
	s_cbranch_vccnz .LBB0_1704
	v_lshl_or_b32 v1, v1, 7, v39
	s_waitcnt lgkmcnt(0)
	v_mov_b32_e32 v2, v248
	v_mov_b32_e32 v3, v249
	v_mul_f32_e32 v0, v3, v0
	v_cndmask_b32_e64 v0, v0, -v0, s[38:39]
	v_fmac_f32_e32 v0, v8, v2
	v_mov_b32_e32 v8, v0

.LBB0_1708:
	s_andn2_b64 vcc, exec, s[20:21]
	s_cbranch_vccnz .LBB0_1710
	v_lshl_or_b32 v1, v1, 7, v39
	s_waitcnt lgkmcnt(0)
	v_mov_b32_e32 v2, v250
	v_mov_b32_e32 v3, v251
	v_mul_f32_e32 v0, v3, v0
	v_cndmask_b32_e64 v0, v0, -v0, s[38:39]
	v_fmac_f32_e32 v0, v9, v2
	v_mov_b32_e32 v9, v0

.LBB0_1714:
	s_andn2_b64 vcc, exec, s[20:21]
	s_cbranch_vccnz .LBB0_1716
	v_lshl_or_b32 v1, v1, 7, v39
	s_waitcnt lgkmcnt(0)
	v_mov_b32_e32 v2, v146
	v_mov_b32_e32 v3, v147
	v_mul_f32_e32 v0, v3, v0
	v_cndmask_b32_e64 v0, v0, -v0, s[38:39]
	v_fmac_f32_e32 v0, v10, v2
	v_mov_b32_e32 v10, v0

.LBB0_1720:
	s_andn2_b64 vcc, exec, s[20:21]
	s_cbranch_vccnz .LBB0_1722
	v_lshl_or_b32 v1, v1, 7, v39
	s_waitcnt lgkmcnt(0)
	v_mov_b32_e32 v2, v148
	v_mov_b32_e32 v3, v149
	v_mul_f32_e32 v0, v3, v0
	v_cndmask_b32_e64 v0, v0, -v0, s[38:39]
	v_fmac_f32_e32 v0, v11, v2
	v_mov_b32_e32 v11, v0

.LBB0_1726:
	s_andn2_b64 vcc, exec, s[20:21]
	s_cbranch_vccnz .LBB0_1728
	v_lshl_or_b32 v1, v1, 7, v39
	s_waitcnt lgkmcnt(0)
	v_mov_b32_e32 v2, v150
	v_mov_b32_e32 v3, v151
	v_mul_f32_e32 v0, v3, v0
	v_cndmask_b32_e64 v0, v0, -v0, s[38:39]
	v_fmac_f32_e32 v0, v12, v2
	v_mov_b32_e32 v12, v0

.LBB0_1732:
	s_andn2_b64 vcc, exec, s[20:21]
	s_cbranch_vccnz .LBB0_1734
	v_lshl_or_b32 v1, v1, 7, v39
	s_waitcnt lgkmcnt(0)
	v_mov_b32_e32 v2, v152
	v_mov_b32_e32 v3, v153
	v_mul_f32_e32 v0, v3, v0
	v_cndmask_b32_e64 v0, v0, -v0, s[38:39]
	v_fmac_f32_e32 v0, v13, v2
	v_mov_b32_e32 v13, v0

.LBB0_1738:
	s_andn2_b64 vcc, exec, s[20:21]
	s_cbranch_vccnz .LBB0_1740
	v_lshl_or_b32 v1, v1, 7, v39
	s_waitcnt lgkmcnt(0)
	v_mov_b32_e32 v2, v154
	v_mov_b32_e32 v3, v155
	v_mul_f32_e32 v0, v3, v0
	v_cndmask_b32_e64 v0, v0, -v0, s[38:39]
	v_fmac_f32_e32 v0, v14, v2
	v_mov_b32_e32 v14, v0

.LBB0_1744:
	s_andn2_b64 vcc, exec, s[20:21]
	s_cbranch_vccnz .LBB0_1185
	v_lshl_or_b32 v1, v1, 7, v39
	s_waitcnt lgkmcnt(0)
	v_mov_b32_e32 v2, v156
	v_mov_b32_e32 v3, v157
	v_mul_f32_e32 v0, v3, v0
	v_cndmask_b32_e64 v0, v0, -v0, s[38:39]
	v_fmac_f32_e32 v0, v15, v2
	v_mov_b32_e32 v15, v0
	s_branch .LBB0_1185
